# out-projection epilogue: residual x rows loaded system-scope nontemporal (read once, keeps the GEMM operand slabs in L2)
# speedup vs baseline: 1.0013x; 1.0013x over previous
; DEV int ltid() { int t = threadIdx.x; asm volatile("" : "+v"(t)); return t; }
; __global__ void __launch_bounds__(256, 2) fwd_megakernel(Params p) {
;     ...
;                 const float* xin = p.x + (size_t)(pm * 2 + h) * 128 * 2048 + pn * 128;
;                 float* ot = p.out + (size_t)(pm * 2 + h) * 128 * 2048 + pn * 128;
;                 stager(smf, 132);
;                 __syncthreads();
;                 const int t2 = ltid(), c4 = t2 & 31, r0 = t2 >> 5;
;                 const float4 g = *(const float4*)(gt1 + c4 * 4);
; #pragma unroll 4
;                 for (int ps = 0; ps < 16; ++ps) {
;                   const int r = ps * 8 + r0;
;                   const float4 sv = *(const float4*)(smf + r * 132 + c4 * 4);
;                   float4 xv = *(const float4*)(xin + (size_t)r * 2048 + c4 * 4);
;                   xv.x += g.x * sv.x; xv.y += g.y * sv.y; xv.z += g.z * sv.z; xv.w += g.w * sv.w;
;                   *(float4*)(ot + (size_t)r * 2048 + c4 * 4) = xv;
;                 }
.LBB0_1252:
	s_mov_b64 s[10:11], 0x0
	v_lshl_add_u64 v[252:253], v[138:139], 0, s[10:11]
	global_load_dwordx4 v[188:191], v[252:253], off sc0 sc1 nt
	s_mov_b64 s[10:11], 0x10000
	v_lshl_add_u64 v[252:253], v[138:139], 0, s[10:11]
	global_load_dwordx4 v[192:195], v[252:253], off sc0 sc1 nt
	s_mov_b64 s[10:11], 0x20000
	v_lshl_add_u64 v[252:253], v[138:139], 0, s[10:11]
	global_load_dwordx4 v[196:199], v[252:253], off sc0 sc1 nt
	s_mov_b64 s[10:11], 0x30000
	v_lshl_add_u64 v[252:253], v[138:139], 0, s[10:11]
	global_load_dwordx4 v[200:203], v[252:253], off sc0 sc1 nt
	s_mov_b64 s[10:11], 0x40000
	v_lshl_add_u64 v[252:253], v[138:139], 0, s[10:11]
	global_load_dwordx4 v[204:207], v[252:253], off sc0 sc1 nt
	s_mov_b64 s[10:11], 0x50000
	v_lshl_add_u64 v[252:253], v[138:139], 0, s[10:11]
	global_load_dwordx4 v[208:211], v[252:253], off sc0 sc1 nt
	s_mov_b64 s[10:11], 0x60000
	v_lshl_add_u64 v[252:253], v[138:139], 0, s[10:11]
	global_load_dwordx4 v[212:215], v[252:253], off sc0 sc1 nt
	s_mov_b64 s[10:11], 0x70000
	v_lshl_add_u64 v[252:253], v[138:139], 0, s[10:11]
	global_load_dwordx4 v[216:219], v[252:253], off sc0 sc1 nt
	ds_read_b128 v[220:223], v140
	ds_read_b128 v[224:227], v140 offset:4224
	s_waitcnt vmcnt(7) lgkmcnt(1)
	v_pk_fma_f32 v[188:189], v[130:131], v[220:221], v[188:189]
	v_pk_fma_f32 v[190:191], v[132:133], v[222:223], v[190:191]
	s_mov_b64 s[10:11], 0x0
	v_lshl_add_u64 v[252:253], v[136:137], 0, s[10:11]
	global_store_dwordx4 v[252:253], v[188:191], off
	ds_read_b128 v[220:223], v140 offset:8448
	s_waitcnt vmcnt(7) lgkmcnt(1)
	v_pk_fma_f32 v[192:193], v[130:131], v[224:225], v[192:193]
	v_pk_fma_f32 v[194:195], v[132:133], v[226:227], v[194:195]
	s_mov_b64 s[10:11], 0x10000
	v_lshl_add_u64 v[252:253], v[136:137], 0, s[10:11]
	global_store_dwordx4 v[252:253], v[192:195], off
	ds_read_b128 v[224:227], v140 offset:12672
	s_waitcnt vmcnt(7) lgkmcnt(1)
	v_pk_fma_f32 v[196:197], v[130:131], v[220:221], v[196:197]
	v_pk_fma_f32 v[198:199], v[132:133], v[222:223], v[198:199]
	s_mov_b64 s[10:11], 0x20000
	v_lshl_add_u64 v[252:253], v[136:137], 0, s[10:11]
	global_store_dwordx4 v[252:253], v[196:199], off
	ds_read_b128 v[220:223], v140 offset:16896
	s_waitcnt vmcnt(7) lgkmcnt(1)
	v_pk_fma_f32 v[200:201], v[130:131], v[224:225], v[200:201]
	v_pk_fma_f32 v[202:203], v[132:133], v[226:227], v[202:203]
	s_mov_b64 s[10:11], 0x30000
	v_lshl_add_u64 v[252:253], v[136:137], 0, s[10:11]
	global_store_dwordx4 v[252:253], v[200:203], off
	ds_read_b128 v[224:227], v140 offset:21120
	s_waitcnt vmcnt(7) lgkmcnt(1)
	v_pk_fma_f32 v[204:205], v[130:131], v[220:221], v[204:205]
	v_pk_fma_f32 v[206:207], v[132:133], v[222:223], v[206:207]
	s_mov_b64 s[10:11], 0x40000
	v_lshl_add_u64 v[252:253], v[136:137], 0, s[10:11]
	global_store_dwordx4 v[252:253], v[204:207], off
	ds_read_b128 v[220:223], v140 offset:25344
	s_waitcnt vmcnt(7) lgkmcnt(1)
	v_pk_fma_f32 v[208:209], v[130:131], v[224:225], v[208:209]
	v_pk_fma_f32 v[210:211], v[132:133], v[226:227], v[210:211]
	s_mov_b64 s[10:11], 0x50000
	v_lshl_add_u64 v[252:253], v[136:137], 0, s[10:11]
	global_store_dwordx4 v[252:253], v[208:211], off
	ds_read_b128 v[224:227], v140 offset:29568
	s_waitcnt vmcnt(7) lgkmcnt(1)
	v_pk_fma_f32 v[212:213], v[130:131], v[220:221], v[212:213]
	v_pk_fma_f32 v[214:215], v[132:133], v[222:223], v[214:215]
	s_mov_b64 s[10:11], 0x60000
	v_lshl_add_u64 v[252:253], v[136:137], 0, s[10:11]
	global_store_dwordx4 v[252:253], v[212:215], off
	s_waitcnt vmcnt(7) lgkmcnt(0)
	v_pk_fma_f32 v[216:217], v[130:131], v[224:225], v[216:217]
	v_pk_fma_f32 v[218:219], v[132:133], v[226:227], v[218:219]
	s_mov_b64 s[10:11], 0x70000
	v_lshl_add_u64 v[252:253], v[136:137], 0, s[10:11]
	global_store_dwordx4 v[252:253], v[216:219], off
	s_mov_b64 s[10:11], 0x80000
	v_lshl_add_u64 v[252:253], v[138:139], 0, s[10:11]
	global_load_dwordx4 v[188:191], v[252:253], off sc0 sc1 nt
	s_mov_b64 s[10:11], 0x90000
	v_lshl_add_u64 v[252:253], v[138:139], 0, s[10:11]
	global_load_dwordx4 v[192:195], v[252:253], off sc0 sc1 nt
	s_mov_b64 s[10:11], 0xa0000
	v_lshl_add_u64 v[252:253], v[138:139], 0, s[10:11]
	global_load_dwordx4 v[196:199], v[252:253], off sc0 sc1 nt
	s_mov_b64 s[10:11], 0xb0000
	v_lshl_add_u64 v[252:253], v[138:139], 0, s[10:11]
	global_load_dwordx4 v[200:203], v[252:253], off sc0 sc1 nt
	s_mov_b64 s[10:11], 0xc0000
	v_lshl_add_u64 v[252:253], v[138:139], 0, s[10:11]
	global_load_dwordx4 v[204:207], v[252:253], off sc0 sc1 nt
	s_mov_b64 s[10:11], 0xd0000
	v_lshl_add_u64 v[252:253], v[138:139], 0, s[10:11]
	global_load_dwordx4 v[208:211], v[252:253], off sc0 sc1 nt
	s_mov_b64 s[10:11], 0xe0000
	v_lshl_add_u64 v[252:253], v[138:139], 0, s[10:11]
	global_load_dwordx4 v[212:215], v[252:253], off sc0 sc1 nt
	s_mov_b64 s[10:11], 0xf0000
	v_lshl_add_u64 v[252:253], v[138:139], 0, s[10:11]
	global_load_dwordx4 v[216:219], v[252:253], off sc0 sc1 nt
	ds_read_b128 v[220:223], v140 offset:33792
	ds_read_b128 v[224:227], v140 offset:38016
	s_waitcnt vmcnt(7) lgkmcnt(1)
	v_pk_fma_f32 v[188:189], v[130:131], v[220:221], v[188:189]
	v_pk_fma_f32 v[190:191], v[132:133], v[222:223], v[190:191]
	s_mov_b64 s[10:11], 0x80000
	v_lshl_add_u64 v[252:253], v[136:137], 0, s[10:11]
	global_store_dwordx4 v[252:253], v[188:191], off
	ds_read_b128 v[220:223], v140 offset:42240
	s_waitcnt vmcnt(7) lgkmcnt(1)
	v_pk_fma_f32 v[192:193], v[130:131], v[224:225], v[192:193]
	v_pk_fma_f32 v[194:195], v[132:133], v[226:227], v[194:195]
	s_mov_b64 s[10:11], 0x90000
	v_lshl_add_u64 v[252:253], v[136:137], 0, s[10:11]
	global_store_dwordx4 v[252:253], v[192:195], off
	ds_read_b128 v[224:227], v140 offset:46464
	s_waitcnt vmcnt(7) lgkmcnt(1)
; DEV int ltid() { int t = threadIdx.x; asm volatile("" : "+v"(t)); return t; }
; template <class AF, class EPI>
; DEV void gemm_tile256(AF aptr, const u16* Bt, int ldb, int K, EPI epi, char* smem) {
;     ...
;       auto stager = [&](float* smf_, int STR) {
;         if (wr == h) {
; #pragma unroll
;           for (int m = 0; m < 8; ++m)
; #pragma unroll
;             for (int n = 0; n < 4; ++n)
; #pragma unroll
;               for (int j = 0; j < 4; ++j) smf_[(m * 16 + fq2 * 4 + j) * STR + wc * 64 + n * 16 + fr2] = acc[m][n][j];
;         }
; __global__ void __launch_bounds__(256, 2) fwd_megakernel(Params p) {
;     ...
;                 const int t2 = ltid(), c4 = t2 & 31, r0 = t2 >> 5;
;                 const float4 g = *(const float4*)(gt1 + c4 * 4);
; #pragma unroll 4
;                 for (int ps = 0; ps < 16; ++ps) {
;                   const int r = ps * 8 + r0;
;                   const float4 sv = *(const float4*)(smf + r * 132 + c4 * 4);
;                   float4 xv = *(const float4*)(xin + (size_t)r * 2048 + c4 * 4);
;                   xv.x += g.x * sv.x; xv.y += g.y * sv.y; xv.z += g.z * sv.z; xv.w += g.w * sv.w;
;                   *(float4*)(ot + (size_t)r * 2048 + c4 * 4) = xv;
;                 }
	v_pk_fma_f32 v[196:197], v[130:131], v[220:221], v[196:197]
	v_pk_fma_f32 v[198:199], v[132:133], v[222:223], v[198:199]
	s_mov_b64 s[10:11], 0xa0000
	v_lshl_add_u64 v[252:253], v[136:137], 0, s[10:11]
	global_store_dwordx4 v[252:253], v[196:199], off
	ds_read_b128 v[220:223], v140 offset:50688
	s_waitcnt vmcnt(7) lgkmcnt(1)
	v_pk_fma_f32 v[200:201], v[130:131], v[224:225], v[200:201]
	v_pk_fma_f32 v[202:203], v[132:133], v[226:227], v[202:203]
	s_mov_b64 s[10:11], 0xb0000
	v_lshl_add_u64 v[252:253], v[136:137], 0, s[10:11]
	global_store_dwordx4 v[252:253], v[200:203], off
	ds_read_b128 v[224:227], v140 offset:54912
	s_waitcnt vmcnt(7) lgkmcnt(1)
	v_pk_fma_f32 v[204:205], v[130:131], v[220:221], v[204:205]
	v_pk_fma_f32 v[206:207], v[132:133], v[222:223], v[206:207]
	s_mov_b64 s[10:11], 0xc0000
	v_lshl_add_u64 v[252:253], v[136:137], 0, s[10:11]
	global_store_dwordx4 v[252:253], v[204:207], off
	ds_read_b128 v[220:223], v140 offset:59136
	s_waitcnt vmcnt(7) lgkmcnt(1)
	v_pk_fma_f32 v[208:209], v[130:131], v[224:225], v[208:209]
	v_pk_fma_f32 v[210:211], v[132:133], v[226:227], v[210:211]
	s_mov_b64 s[10:11], 0xd0000
	v_lshl_add_u64 v[252:253], v[136:137], 0, s[10:11]
	global_store_dwordx4 v[252:253], v[208:211], off
	ds_read_b128 v[224:227], v140 offset:63360
	s_waitcnt vmcnt(7) lgkmcnt(1)
	v_pk_fma_f32 v[212:213], v[130:131], v[220:221], v[212:213]
	v_pk_fma_f32 v[214:215], v[132:133], v[222:223], v[214:215]
	s_mov_b64 s[10:11], 0xe0000
	v_lshl_add_u64 v[252:253], v[136:137], 0, s[10:11]
	global_store_dwordx4 v[252:253], v[212:215], off
	s_waitcnt vmcnt(7) lgkmcnt(0)
	v_pk_fma_f32 v[216:217], v[130:131], v[224:225], v[216:217]
	v_pk_fma_f32 v[218:219], v[132:133], v[226:227], v[218:219]
	s_mov_b64 s[10:11], 0xf0000
	v_lshl_add_u64 v[252:253], v[136:137], 0, s[10:11]
	global_store_dwordx4 v[252:253], v[216:219], off
	v_cmp_eq_u32_e32 vcc, 1, v1
	s_barrier
	s_and_saveexec_b64 s[10:11], vcc
	s_cbranch_execz .LBB0_1255
	ds_write2_b32 v187, v127, v128 offset0:4 offset1:136
	ds_write_b32 v177, v129 offset:1584
	ds_write2_b32 v177, v126, v122 offset1:16
	ds_write_b32 v178, v123 offset:64
	ds_write_b32 v179, v124 offset:64
	ds_write_b32 v180, v125 offset:64
	ds_write_b32 v177, v118 offset:128
	ds_write_b32 v178, v119 offset:128
	ds_write_b32 v179, v120 offset:128
	ds_write_b32 v180, v121 offset:128
	ds_write_b32 v177, v114 offset:192
	ds_write_b32 v178, v115 offset:192
	ds_write_b32 v179, v116 offset:192
	ds_write_b32 v180, v117 offset:192
	ds_write2_b32 v185, v110, v111 offset0:64 offset1:196
	ds_write2_b32 v186, v112, v113 offset0:72 offset1:204
	ds_write_b32 v171, v106 offset:64
	ds_write_b32 v172, v107 offset:64
	ds_write_b32 v173, v108 offset:64
	ds_write_b32 v174, v109 offset:64
	ds_write_b32 v171, v102 offset:128
	ds_write_b32 v172, v103 offset:128
	ds_write_b32 v173, v104 offset:128
	ds_write_b32 v174, v105 offset:128
	ds_write_b32 v171, v98 offset:192
	ds_write_b32 v172, v99 offset:192
	ds_write_b32 v173, v100 offset:192
	ds_write_b32 v174, v101 offset:192
	ds_write2_b32 v183, v94, v95 offset1:132
	ds_write2_b32 v184, v96, v97 offset0:8 offset1:140
	ds_write_b32 v165, v42 offset:64
	ds_write_b32 v166, v43 offset:64
	ds_write_b32 v167, v44 offset:64
	ds_write_b32 v168, v45 offset:64
	ds_write_b32 v165, v38 offset:128
	ds_write_b32 v166, v39 offset:128
	ds_write_b32 v167, v40 offset:128
	ds_write_b32 v168, v41 offset:128
	ds_write_b32 v165, v34 offset:192
	ds_write_b32 v166, v35 offset:192
	ds_write_b32 v167, v36 offset:192
	ds_write_b32 v168, v37 offset:192
	ds_write2_b32 v181, v30, v31 offset0:64 offset1:196
	ds_write2_b32 v182, v32, v33 offset0:72 offset1:204
	ds_write_b32 v161, v26 offset:64
	ds_write_b32 v162, v27 offset:64
	ds_write_b32 v163, v28 offset:64
	ds_write_b32 v164, v29 offset:64
	ds_write_b32 v161, v22 offset:128
	ds_write_b32 v162, v23 offset:128
	ds_write_b32 v163, v24 offset:128
	ds_write_b32 v164, v25 offset:128
	ds_write_b32 v161, v18 offset:192
	ds_write_b32 v162, v19 offset:192
	ds_write_b32 v163, v20 offset:192
	ds_write_b32 v164, v21 offset:192
	ds_write2_b32 v175, v14, v15 offset1:132
	ds_write2_b32 v176, v16, v17 offset0:8 offset1:140
	ds_write_b32 v155, v10 offset:64
	ds_write_b32 v156, v11 offset:64
	ds_write_b32 v157, v12 offset:64
	ds_write_b32 v158, v13 offset:64
	ds_write_b32 v155, v6 offset:128
	ds_write_b32 v156, v7 offset:128
	ds_write_b32 v157, v8 offset:128
	ds_write_b32 v158, v9 offset:128
	ds_write_b32 v155, v2 offset:192
	ds_write_b32 v156, v3 offset:192
	ds_write_b32 v157, v4 offset:192
	ds_write_b32 v158, v5 offset:192
	ds_write2_b32 v169, v46, v47 offset0:64 offset1:196
	ds_write2_b32 v170, v48, v49 offset0:72 offset1:204
	ds_write_b32 v149, v50 offset:64
	ds_write_b32 v150, v51 offset:64
	ds_write_b32 v151, v52 offset:64
	ds_write_b32 v152, v53 offset:64
	ds_write_b32 v149, v54 offset:128
	ds_write_b32 v150, v55 offset:128
	ds_write_b32 v151, v56 offset:128
	ds_write_b32 v152, v57 offset:128
	ds_write_b32 v149, v58 offset:192
	ds_write_b32 v150, v59 offset:192
	ds_write_b32 v151, v60 offset:192
	ds_write_b32 v152, v61 offset:192
	ds_write2_b32 v159, v62, v63 offset1:132
	ds_write2_b32 v160, v64, v65 offset0:8 offset1:140
	ds_write_b32 v145, v66 offset:64
	ds_write_b32 v146, v67 offset:64
	ds_write_b32 v147, v68 offset:64
	ds_write_b32 v148, v69 offset:64
	ds_write_b32 v145, v70 offset:128
	ds_write_b32 v146, v71 offset:128
	ds_write_b32 v147, v72 offset:128
	ds_write_b32 v148, v73 offset:128
	ds_write_b32 v145, v74 offset:192
	ds_write_b32 v146, v75 offset:192
	ds_write_b32 v147, v76 offset:192
	ds_write_b32 v148, v77 offset:192
	ds_write2_b32 v153, v78, v79 offset0:64 offset1:196
	ds_write2_b32 v154, v80, v81 offset0:72 offset1:204
	ds_write_b32 v134, v82 offset:64
	ds_write_b32 v142, v83 offset:64
	ds_write_b32 v143, v84 offset:64
	ds_write_b32 v144, v85 offset:64
	ds_write_b32 v134, v86 offset:128
	ds_write_b32 v142, v87 offset:128
	ds_write_b32 v143, v88 offset:128
	ds_write_b32 v144, v89 offset:128
	ds_write_b32 v134, v90 offset:192
	ds_write_b32 v142, v91 offset:192
	ds_write_b32 v143, v92 offset:192
	ds_write_b32 v144, v93 offset:192

; DEV int ltid() { int t = threadIdx.x; asm volatile("" : "+v"(t)); return t; }
; __global__ void __launch_bounds__(256, 2) fwd_megakernel(Params p) {
;     ...
;                 const float* xin = p.x + (size_t)(pm * 2 + h) * 128 * 2048 + pn * 128;
;                 float* ot = p.out + (size_t)(pm * 2 + h) * 128 * 2048 + pn * 128;
;                 stager(smf, 132);
;                 __syncthreads();
;                 const int t2 = ltid(), c4 = t2 & 31, r0 = t2 >> 5;
;                 const float4 g = *(const float4*)(gt1 + c4 * 4);
; #pragma unroll 4
;                 for (int ps = 0; ps < 16; ++ps) {
;                   const int r = ps * 8 + r0;
;                   const float4 sv = *(const float4*)(smf + r * 132 + c4 * 4);
;                   float4 xv = *(const float4*)(xin + (size_t)r * 2048 + c4 * 4);
;                   xv.x += g.x * sv.x; xv.y += g.y * sv.y; xv.z += g.z * sv.z; xv.w += g.w * sv.w;
;                   *(float4*)(ot + (size_t)r * 2048 + c4 * 4) = xv;
;                 }
.LBB0_1256:
	s_mov_b64 s[6:7], 0x100000
	v_lshl_add_u64 v[252:253], v[8:9], 0, s[6:7]
	global_load_dwordx4 v[188:191], v[252:253], off sc0 sc1 nt
	s_mov_b64 s[6:7], 0x110000
	v_lshl_add_u64 v[252:253], v[8:9], 0, s[6:7]
	global_load_dwordx4 v[192:195], v[252:253], off sc0 sc1 nt
	s_mov_b64 s[6:7], 0x120000
	v_lshl_add_u64 v[252:253], v[8:9], 0, s[6:7]
	global_load_dwordx4 v[196:199], v[252:253], off sc0 sc1 nt
	s_mov_b64 s[6:7], 0x130000
	v_lshl_add_u64 v[252:253], v[8:9], 0, s[6:7]
	global_load_dwordx4 v[200:203], v[252:253], off sc0 sc1 nt
	s_mov_b64 s[6:7], 0x140000
	v_lshl_add_u64 v[252:253], v[8:9], 0, s[6:7]
	global_load_dwordx4 v[204:207], v[252:253], off sc0 sc1 nt
	s_mov_b64 s[6:7], 0x150000
	v_lshl_add_u64 v[252:253], v[8:9], 0, s[6:7]
	global_load_dwordx4 v[208:211], v[252:253], off sc0 sc1 nt
	s_mov_b64 s[6:7], 0x160000
	v_lshl_add_u64 v[252:253], v[8:9], 0, s[6:7]
	global_load_dwordx4 v[212:215], v[252:253], off sc0 sc1 nt
	s_mov_b64 s[6:7], 0x170000
	v_lshl_add_u64 v[252:253], v[8:9], 0, s[6:7]
	global_load_dwordx4 v[216:219], v[252:253], off sc0 sc1 nt
	ds_read_b128 v[220:223], v10
	ds_read_b128 v[224:227], v10 offset:4224
	s_waitcnt vmcnt(7) lgkmcnt(1)
	v_pk_fma_f32 v[188:189], v[2:3], v[220:221], v[188:189]
	v_pk_fma_f32 v[190:191], v[4:5], v[222:223], v[190:191]
	s_mov_b64 s[6:7], 0x100000
	v_lshl_add_u64 v[252:253], v[6:7], 0, s[6:7]
	global_store_dwordx4 v[252:253], v[188:191], off
	ds_read_b128 v[220:223], v10 offset:8448
	s_waitcnt vmcnt(7) lgkmcnt(1)
	v_pk_fma_f32 v[192:193], v[2:3], v[224:225], v[192:193]
	v_pk_fma_f32 v[194:195], v[4:5], v[226:227], v[194:195]
	s_mov_b64 s[6:7], 0x110000
	v_lshl_add_u64 v[252:253], v[6:7], 0, s[6:7]
	global_store_dwordx4 v[252:253], v[192:195], off
	ds_read_b128 v[224:227], v10 offset:12672
	s_waitcnt vmcnt(7) lgkmcnt(1)
	v_pk_fma_f32 v[196:197], v[2:3], v[220:221], v[196:197]
	v_pk_fma_f32 v[198:199], v[4:5], v[222:223], v[198:199]
	s_mov_b64 s[6:7], 0x120000
	v_lshl_add_u64 v[252:253], v[6:7], 0, s[6:7]
	global_store_dwordx4 v[252:253], v[196:199], off
	ds_read_b128 v[220:223], v10 offset:16896
	s_waitcnt vmcnt(7) lgkmcnt(1)
	v_pk_fma_f32 v[200:201], v[2:3], v[224:225], v[200:201]
	v_pk_fma_f32 v[202:203], v[4:5], v[226:227], v[202:203]
	s_mov_b64 s[6:7], 0x130000
	v_lshl_add_u64 v[252:253], v[6:7], 0, s[6:7]
	global_store_dwordx4 v[252:253], v[200:203], off
	ds_read_b128 v[224:227], v10 offset:21120
	s_waitcnt vmcnt(7) lgkmcnt(1)
	v_pk_fma_f32 v[204:205], v[2:3], v[220:221], v[204:205]
	v_pk_fma_f32 v[206:207], v[4:5], v[222:223], v[206:207]
	s_mov_b64 s[6:7], 0x140000
	v_lshl_add_u64 v[252:253], v[6:7], 0, s[6:7]
	global_store_dwordx4 v[252:253], v[204:207], off
	ds_read_b128 v[220:223], v10 offset:25344
	s_waitcnt vmcnt(7) lgkmcnt(1)
	v_pk_fma_f32 v[208:209], v[2:3], v[224:225], v[208:209]
	v_pk_fma_f32 v[210:211], v[4:5], v[226:227], v[210:211]
	s_mov_b64 s[6:7], 0x150000
	v_lshl_add_u64 v[252:253], v[6:7], 0, s[6:7]
	global_store_dwordx4 v[252:253], v[208:211], off
	ds_read_b128 v[224:227], v10 offset:29568
	s_waitcnt vmcnt(7) lgkmcnt(1)
	v_pk_fma_f32 v[212:213], v[2:3], v[220:221], v[212:213]
	v_pk_fma_f32 v[214:215], v[4:5], v[222:223], v[214:215]
	s_mov_b64 s[6:7], 0x160000
	v_lshl_add_u64 v[252:253], v[6:7], 0, s[6:7]
	global_store_dwordx4 v[252:253], v[212:215], off
	s_waitcnt vmcnt(7) lgkmcnt(0)
; DEV int ltid() { int t = threadIdx.x; asm volatile("" : "+v"(t)); return t; }
; __global__ void __launch_bounds__(256, 2) fwd_megakernel(Params p) {
;     ...
;                 const float* xin = p.x + (size_t)(pm * 2 + h) * 128 * 2048 + pn * 128;
;                 float* ot = p.out + (size_t)(pm * 2 + h) * 128 * 2048 + pn * 128;
;                 stager(smf, 132);
;                 __syncthreads();
;                 const int t2 = ltid(), c4 = t2 & 31, r0 = t2 >> 5;
;                 const float4 g = *(const float4*)(gt1 + c4 * 4);
; #pragma unroll 4
;                 for (int ps = 0; ps < 16; ++ps) {
;                   const int r = ps * 8 + r0;
;                   const float4 sv = *(const float4*)(smf + r * 132 + c4 * 4);
;                   float4 xv = *(const float4*)(xin + (size_t)r * 2048 + c4 * 4);
;                   xv.x += g.x * sv.x; xv.y += g.y * sv.y; xv.z += g.z * sv.z; xv.w += g.w * sv.w;
;                   *(float4*)(ot + (size_t)r * 2048 + c4 * 4) = xv;
;                 }
;                 __syncthreads();
;               }, smem);
;   }
	v_pk_fma_f32 v[216:217], v[2:3], v[224:225], v[216:217]
	v_pk_fma_f32 v[218:219], v[4:5], v[226:227], v[218:219]
	s_mov_b64 s[6:7], 0x170000
	v_lshl_add_u64 v[252:253], v[6:7], 0, s[6:7]
	global_store_dwordx4 v[252:253], v[216:219], off
	s_mov_b64 s[6:7], 0x180000
	v_lshl_add_u64 v[252:253], v[8:9], 0, s[6:7]
	global_load_dwordx4 v[188:191], v[252:253], off sc0 sc1 nt
	s_mov_b64 s[6:7], 0x190000
	v_lshl_add_u64 v[252:253], v[8:9], 0, s[6:7]
	global_load_dwordx4 v[192:195], v[252:253], off sc0 sc1 nt
	s_mov_b64 s[6:7], 0x1a0000
	v_lshl_add_u64 v[252:253], v[8:9], 0, s[6:7]
	global_load_dwordx4 v[196:199], v[252:253], off sc0 sc1 nt
	s_mov_b64 s[6:7], 0x1b0000
	v_lshl_add_u64 v[252:253], v[8:9], 0, s[6:7]
	global_load_dwordx4 v[200:203], v[252:253], off sc0 sc1 nt
	s_mov_b64 s[6:7], 0x1c0000
	v_lshl_add_u64 v[252:253], v[8:9], 0, s[6:7]
	global_load_dwordx4 v[204:207], v[252:253], off sc0 sc1 nt
	s_mov_b64 s[6:7], 0x1d0000
	v_lshl_add_u64 v[252:253], v[8:9], 0, s[6:7]
	global_load_dwordx4 v[208:211], v[252:253], off sc0 sc1 nt
	s_mov_b64 s[6:7], 0x1e0000
	v_lshl_add_u64 v[252:253], v[8:9], 0, s[6:7]
	global_load_dwordx4 v[212:215], v[252:253], off sc0 sc1 nt
	s_mov_b64 s[6:7], 0x1f0000
	v_lshl_add_u64 v[252:253], v[8:9], 0, s[6:7]
	global_load_dwordx4 v[216:219], v[252:253], off sc0 sc1 nt
	ds_read_b128 v[220:223], v10 offset:33792
	ds_read_b128 v[224:227], v10 offset:38016
	s_waitcnt vmcnt(7) lgkmcnt(1)
	v_pk_fma_f32 v[188:189], v[2:3], v[220:221], v[188:189]
	v_pk_fma_f32 v[190:191], v[4:5], v[222:223], v[190:191]
	s_mov_b64 s[6:7], 0x180000
	v_lshl_add_u64 v[252:253], v[6:7], 0, s[6:7]
	global_store_dwordx4 v[252:253], v[188:191], off
	ds_read_b128 v[220:223], v10 offset:42240
	s_waitcnt vmcnt(7) lgkmcnt(1)
	v_pk_fma_f32 v[192:193], v[2:3], v[224:225], v[192:193]
	v_pk_fma_f32 v[194:195], v[4:5], v[226:227], v[194:195]
	s_mov_b64 s[6:7], 0x190000
	v_lshl_add_u64 v[252:253], v[6:7], 0, s[6:7]
	global_store_dwordx4 v[252:253], v[192:195], off
	ds_read_b128 v[224:227], v10 offset:46464
	s_waitcnt vmcnt(7) lgkmcnt(1)
	v_pk_fma_f32 v[196:197], v[2:3], v[220:221], v[196:197]
	v_pk_fma_f32 v[198:199], v[4:5], v[222:223], v[198:199]
	s_mov_b64 s[6:7], 0x1a0000
	v_lshl_add_u64 v[252:253], v[6:7], 0, s[6:7]
	global_store_dwordx4 v[252:253], v[196:199], off
	ds_read_b128 v[220:223], v10 offset:50688
	s_waitcnt vmcnt(7) lgkmcnt(1)
	v_pk_fma_f32 v[200:201], v[2:3], v[224:225], v[200:201]
	v_pk_fma_f32 v[202:203], v[4:5], v[226:227], v[202:203]
	s_mov_b64 s[6:7], 0x1b0000
	v_lshl_add_u64 v[252:253], v[6:7], 0, s[6:7]
	global_store_dwordx4 v[252:253], v[200:203], off
	ds_read_b128 v[224:227], v10 offset:54912
	s_waitcnt vmcnt(7) lgkmcnt(1)
	v_pk_fma_f32 v[204:205], v[2:3], v[220:221], v[204:205]
	v_pk_fma_f32 v[206:207], v[4:5], v[222:223], v[206:207]
	s_mov_b64 s[6:7], 0x1c0000
	v_lshl_add_u64 v[252:253], v[6:7], 0, s[6:7]
	global_store_dwordx4 v[252:253], v[204:207], off
	ds_read_b128 v[220:223], v10 offset:59136
	s_waitcnt vmcnt(7) lgkmcnt(1)
	v_pk_fma_f32 v[208:209], v[2:3], v[224:225], v[208:209]
	v_pk_fma_f32 v[210:211], v[4:5], v[226:227], v[210:211]
	s_mov_b64 s[6:7], 0x1d0000
	v_lshl_add_u64 v[252:253], v[6:7], 0, s[6:7]
	global_store_dwordx4 v[252:253], v[208:211], off
	ds_read_b128 v[224:227], v10 offset:63360
	s_waitcnt vmcnt(7) lgkmcnt(1)
	v_pk_fma_f32 v[212:213], v[2:3], v[220:221], v[212:213]
	v_pk_fma_f32 v[214:215], v[4:5], v[222:223], v[214:215]
	s_mov_b64 s[6:7], 0x1e0000
	v_lshl_add_u64 v[252:253], v[6:7], 0, s[6:7]
	global_store_dwordx4 v[252:253], v[212:215], off
	s_waitcnt vmcnt(7) lgkmcnt(0)
	v_pk_fma_f32 v[216:217], v[2:3], v[224:225], v[216:217]
	v_pk_fma_f32 v[218:219], v[4:5], v[226:227], v[218:219]
	s_mov_b64 s[6:7], 0x1f0000
	v_lshl_add_u64 v[252:253], v[6:7], 0, s[6:7]
	global_store_dwordx4 v[252:253], v[216:219], off
	s_lshr_b32 s6, s92, 3
	s_add_i32 s24, s24, s13
	s_add_i32 s3, s3, s6
	s_cmpk_gt_i32 s24, 0x7f
	s_barrier
	s_cbranch_scc0 .LBB0_1241
